# baseline (speedup 1.0000x reference)
; #define LDA(dst, b, h) for (int m = 0; m < 4; ++m) for (int k = 0; k < 2; ++k) \
;     dst[m][k] = *reinterpret_cast<const bf16x8*>((char*)SA(b, h) + aoff + m * 2048 + k * 1024)
; #define LDB(dst, b, h) for (int n = 0; n < 2; ++n) for (int k = 0; k < 2; ++k) \
;     dst[n][k] = *reinterpret_cast<const bf16x8*>((char*)SB(b, h) + boff + n * 2048 + k * 1024)
; #define MMA(ai, bj, At, Bt) do { __builtin_amdgcn_s_setprio(1); \
;     for (int m = 0; m < 4; ++m) for (int n = 0; n < 2; ++n) for (int k = 0; k < 2; ++k) \
;       acc[ai][bj][m][n] = __builtin_amdgcn_mfma_f32_16x16x32_bf16(Bt[n][k], At[m][k], acc[ai][bj][m][n], 0, 0, 0); \
;     __builtin_amdgcn_s_setprio(0); } while (0)
; #define WAIT_V(n) asm volatile("s_waitcnt vmcnt(" #n ")" ::: "memory")
; #define WAIT_L(n) asm volatile("s_waitcnt lgkmcnt(" #n ")" ::: "memory")
; #define BAR __builtin_amdgcn_s_barrier()
; #define SCHED __builtin_amdgcn_sched_barrier(0)
; DEV void gemm_core(const u16* __restrict__ A, int lda, const u16* __restrict__ Bt, int ldb, int K,
;                    int brow, int bcol, f32x4 (&acc)[2][2][4][2]) {
;     ...
;     LDB(B0, 0, 0); SCHED; LDA(At, 0, 0); STAGE(SA(1, 1), A, lda, brow + HALF, t + 1);
;     WAIT_L(8); BAR; WAIT_L(0); MMA(0, 0, At, B0); BAR; SCHED;
;     LDB(B1, 0, 1); STAGE(SB(0, 0), Bt, ldb, bcol, t + 2);
;     BAR; WAIT_L(0); MMA(0, 1, At, B1); BAR;
;     LDA(At, 0, 1); STAGE(SA(0, 0), A, lda, brow, t + 2);
;     BAR; WAIT_L(0); MMA(1, 0, At, B0); BAR; SCHED;
;     STAGE(SB(0, 1), Bt, ldb, bcol + HALF, t + 2);
;     WAIT_V(6); BAR; MMA(1, 1, At, B1); BAR;
.LBB0_191:
	ds_read_b128 v[162:165], v199
	ds_read_b128 v[166:169], v199 offset:1024
	ds_read_b128 v[170:173], v199 offset:2048
	ds_read_b128 v[174:177], v199 offset:3072
	global_load_lds_dwordx4 v153, s[6:7]
	s_add_i32 m0, s38, 0xe000
	ds_read_b128 v[200:203], v197
	global_load_lds_dwordx4 v152, s[6:7]
	ds_read_b128 v[204:207], v197 offset:1024
	ds_read_b128 v[208:211], v197 offset:2048
	ds_read_b128 v[212:215], v197 offset:3072
	ds_read_b128 v[216:219], v197 offset:4096
	ds_read_b128 v[220:223], v197 offset:5120
	ds_read_b128 v[224:227], v197 offset:6144
	ds_read_b128 v[228:231], v197 offset:7168
	s_waitcnt lgkmcnt(8)
	s_barrier
	s_waitcnt lgkmcnt(0)
	v_mfma_f32_16x16x32_bf16 v[0:3], v[162:165], v[200:203], v[0:3]
	v_mfma_f32_16x16x32_bf16 v[126:129], v[170:173], v[200:203], v[126:129]
	v_mfma_f32_16x16x32_bf16 v[122:125], v[162:165], v[208:211], v[122:125]
	v_mfma_f32_16x16x32_bf16 v[118:121], v[170:173], v[208:211], v[118:121]
	v_mfma_f32_16x16x32_bf16 v[114:117], v[162:165], v[216:219], v[114:117]
	v_mfma_f32_16x16x32_bf16 v[110:113], v[170:173], v[216:219], v[110:113]
	v_mfma_f32_16x16x32_bf16 v[106:109], v[162:165], v[224:227], v[106:109]
	v_mfma_f32_16x16x32_bf16 v[102:105], v[170:173], v[224:227], v[102:105]
	v_mfma_f32_16x16x32_bf16 v[0:3], v[166:169], v[204:207], v[0:3]
	v_mfma_f32_16x16x32_bf16 v[126:129], v[174:177], v[204:207], v[126:129]
	v_mfma_f32_16x16x32_bf16 v[122:125], v[166:169], v[212:215], v[122:125]
	v_mfma_f32_16x16x32_bf16 v[118:121], v[174:177], v[212:215], v[118:121]
	v_mfma_f32_16x16x32_bf16 v[114:117], v[166:169], v[220:223], v[114:117]
	v_mfma_f32_16x16x32_bf16 v[110:113], v[174:177], v[220:223], v[110:113]
	v_mfma_f32_16x16x32_bf16 v[106:109], v[166:169], v[228:231], v[106:109]
	v_mfma_f32_16x16x32_bf16 v[102:105], v[174:177], v[228:231], v[102:105]
	v_add_u32_e32 v153, 0x80, v153
	v_add_u32_e32 v152, 0x80, v152
	s_add_i32 m0, s38, 0x10000
	s_barrier
	global_load_lds_dwordx4 v159, s[8:9]
	s_add_i32 m0, s38, 0x12000
	ds_read_b128 v[232:235], v250
	global_load_lds_dwordx4 v158, s[8:9]
	ds_read_b128 v[236:239], v250 offset:1024
	ds_read_b128 v[240:243], v250 offset:2048
	ds_read_b128 v[244:247], v250 offset:3072
	s_add_i32 s36, s36, 2
	s_barrier
	s_waitcnt lgkmcnt(0)
	v_mfma_f32_16x16x32_bf16 v[98:101], v[232:235], v[200:203], v[98:101]
	v_mfma_f32_16x16x32_bf16 v[94:97], v[240:243], v[200:203], v[94:97]
	v_mfma_f32_16x16x32_bf16 v[90:93], v[232:235], v[208:211], v[90:93]
	v_mfma_f32_16x16x32_bf16 v[86:89], v[240:243], v[208:211], v[86:89]
	v_mfma_f32_16x16x32_bf16 v[82:85], v[232:235], v[216:219], v[82:85]
	v_mfma_f32_16x16x32_bf16 v[78:81], v[240:243], v[216:219], v[78:81]
	v_mfma_f32_16x16x32_bf16 v[74:77], v[232:235], v[224:227], v[74:77]
	v_mfma_f32_16x16x32_bf16 v[70:73], v[240:243], v[224:227], v[70:73]
	v_mfma_f32_16x16x32_bf16 v[98:101], v[236:239], v[204:207], v[98:101]
	v_mfma_f32_16x16x32_bf16 v[94:97], v[244:247], v[204:207], v[94:97]
	v_mfma_f32_16x16x32_bf16 v[90:93], v[236:239], v[212:215], v[90:93]
	v_mfma_f32_16x16x32_bf16 v[86:89], v[244:247], v[212:215], v[86:89]
	v_mfma_f32_16x16x32_bf16 v[82:85], v[236:239], v[220:223], v[82:85]
	v_mfma_f32_16x16x32_bf16 v[78:81], v[244:247], v[220:223], v[78:81]
	v_mfma_f32_16x16x32_bf16 v[74:77], v[236:239], v[228:231], v[74:77]
	v_mfma_f32_16x16x32_bf16 v[70:73], v[244:247], v[228:231], v[70:73]
	v_add_u32_e32 v159, 0x80, v159
	v_add_u32_e32 v158, 0x80, v158
	s_mov_b32 m0, s38
	s_barrier
	global_load_lds_dwordx4 v157, s[6:7]
	s_add_i32 m0, s38, 0x2000
	ds_read_b128 v[200:203], v197 offset:16384
	global_load_lds_dwordx4 v156, s[6:7]
	ds_read_b128 v[204:207], v197 offset:17408
	ds_read_b128 v[208:211], v197 offset:18432
	ds_read_b128 v[212:215], v197 offset:19456
	ds_read_b128 v[216:219], v197 offset:20480
	ds_read_b128 v[220:223], v197 offset:21504
	ds_read_b128 v[224:227], v197 offset:22528
	ds_read_b128 v[228:231], v197 offset:23552
	s_barrier
	s_waitcnt lgkmcnt(0)
	v_mfma_f32_16x16x32_bf16 v[66:69], v[162:165], v[200:203], v[66:69]
	v_mfma_f32_16x16x32_bf16 v[62:65], v[170:173], v[200:203], v[62:65]
	v_mfma_f32_16x16x32_bf16 v[58:61], v[162:165], v[208:211], v[58:61]
	v_mfma_f32_16x16x32_bf16 v[54:57], v[170:173], v[208:211], v[54:57]
	v_mfma_f32_16x16x32_bf16 v[50:53], v[162:165], v[216:219], v[50:53]
	v_mfma_f32_16x16x32_bf16 v[46:49], v[170:173], v[216:219], v[46:49]
	v_mfma_f32_16x16x32_bf16 v[42:45], v[162:165], v[224:227], v[42:45]
	v_mfma_f32_16x16x32_bf16 v[38:41], v[170:173], v[224:227], v[38:41]
	v_mfma_f32_16x16x32_bf16 v[66:69], v[166:169], v[204:207], v[66:69]
	v_mfma_f32_16x16x32_bf16 v[62:65], v[174:177], v[204:207], v[62:65]
	v_mfma_f32_16x16x32_bf16 v[58:61], v[166:169], v[212:215], v[58:61]
	v_mfma_f32_16x16x32_bf16 v[54:57], v[174:177], v[212:215], v[54:57]
	v_mfma_f32_16x16x32_bf16 v[50:53], v[166:169], v[220:223], v[50:53]
	v_mfma_f32_16x16x32_bf16 v[46:49], v[174:177], v[220:223], v[46:49]
	v_mfma_f32_16x16x32_bf16 v[42:45], v[166:169], v[228:231], v[42:45]
	v_mfma_f32_16x16x32_bf16 v[38:41], v[174:177], v[228:231], v[38:41]
	v_add_u32_e32 v157, 0x80, v157
	v_add_u32_e32 v156, 0x80, v156
	s_add_i32 m0, s38, 0x14000
	s_barrier
	global_load_lds_dwordx4 v155, s[8:9]
	s_add_i32 m0, s38, 0x16000
	s_nop 0
	global_load_lds_dwordx4 v154, s[8:9]
	s_waitcnt vmcnt(6)
	s_barrier
; #define LDA(dst, b, h) for (int m = 0; m < 4; ++m) for (int k = 0; k < 2; ++k) \
;     dst[m][k] = *reinterpret_cast<const bf16x8*>((char*)SA(b, h) + aoff + m * 2048 + k * 1024)
; #define LDB(dst, b, h) for (int n = 0; n < 2; ++n) for (int k = 0; k < 2; ++k) \
;     dst[n][k] = *reinterpret_cast<const bf16x8*>((char*)SB(b, h) + boff + n * 2048 + k * 1024)
; #define MMA(ai, bj, At, Bt) do { __builtin_amdgcn_s_setprio(1); \
;     for (int m = 0; m < 4; ++m) for (int n = 0; n < 2; ++n) for (int k = 0; k < 2; ++k) \
;       acc[ai][bj][m][n] = __builtin_amdgcn_mfma_f32_16x16x32_bf16(Bt[n][k], At[m][k], acc[ai][bj][m][n], 0, 0, 0); \
;     __builtin_amdgcn_s_setprio(0); } while (0)
; #define WAIT_V(n) asm volatile("s_waitcnt vmcnt(" #n ")" ::: "memory")
; #define WAIT_L(n) asm volatile("s_waitcnt lgkmcnt(" #n ")" ::: "memory")
; #define BAR __builtin_amdgcn_s_barrier()
; #define SCHED __builtin_amdgcn_sched_barrier(0)
; DEV void gemm_core(const u16* __restrict__ A, int lda, const u16* __restrict__ Bt, int ldb, int K,
;                    int brow, int bcol, f32x4 (&acc)[2][2][4][2]) {
;     ...
;     WAIT_V(6); BAR; MMA(1, 1, At, B1); BAR;
;     LDB(B0, 1, 0); SCHED; LDA(At, 1, 0); STAGE(SA(0, 1), A, lda, brow + HALF, t + 2);
;     WAIT_L(8); BAR; WAIT_L(0); MMA(0, 0, At, B0); BAR; SCHED;
;     LDB(B1, 1, 1); STAGE(SB(1, 0), Bt, ldb, bcol, t + 3);
;     BAR; WAIT_L(0); MMA(0, 1, At, B1); BAR;
;     LDA(At, 1, 1); STAGE(SA(1, 0), A, lda, brow, t + 3);
	v_mfma_f32_16x16x32_bf16 v[34:37], v[232:235], v[200:203], v[34:37]
	v_mfma_f32_16x16x32_bf16 v[30:33], v[240:243], v[200:203], v[30:33]
	v_mfma_f32_16x16x32_bf16 v[26:29], v[232:235], v[208:211], v[26:29]
	v_mfma_f32_16x16x32_bf16 v[22:25], v[240:243], v[208:211], v[22:25]
	v_mfma_f32_16x16x32_bf16 v[18:21], v[232:235], v[216:219], v[18:21]
	v_mfma_f32_16x16x32_bf16 v[14:17], v[240:243], v[216:219], v[14:17]
	v_mfma_f32_16x16x32_bf16 v[10:13], v[232:235], v[224:227], v[10:13]
	v_mfma_f32_16x16x32_bf16 v[6:9], v[240:243], v[224:227], v[6:9]
	v_mfma_f32_16x16x32_bf16 v[34:37], v[236:239], v[204:207], v[34:37]
	v_mfma_f32_16x16x32_bf16 v[30:33], v[244:247], v[204:207], v[30:33]
	v_mfma_f32_16x16x32_bf16 v[26:29], v[236:239], v[212:215], v[26:29]
	v_mfma_f32_16x16x32_bf16 v[22:25], v[244:247], v[212:215], v[22:25]
	v_mfma_f32_16x16x32_bf16 v[18:21], v[236:239], v[220:223], v[18:21]
	v_mfma_f32_16x16x32_bf16 v[14:17], v[244:247], v[220:223], v[14:17]
	v_mfma_f32_16x16x32_bf16 v[10:13], v[236:239], v[228:231], v[10:13]
	v_mfma_f32_16x16x32_bf16 v[6:9], v[244:247], v[228:231], v[6:9]
	v_add_u32_e32 v155, 0x80, v155
	v_add_u32_e32 v154, 0x80, v154
	s_add_i32 m0, s38, 0x4000
	s_barrier
	ds_read_b128 v[162:165], v251
	ds_read_b128 v[166:169], v251 offset:1024
	ds_read_b128 v[170:173], v251 offset:2048
	ds_read_b128 v[174:177], v251 offset:3072
	global_load_lds_dwordx4 v153, s[6:7]
	s_add_i32 m0, s38, 0x6000
	ds_read_b128 v[200:203], v197 offset:32768
	global_load_lds_dwordx4 v152, s[6:7]
	ds_read_b128 v[204:207], v197 offset:33792
	ds_read_b128 v[208:211], v197 offset:34816
	ds_read_b128 v[212:215], v197 offset:35840
	ds_read_b128 v[216:219], v197 offset:36864
	ds_read_b128 v[220:223], v197 offset:37888
	ds_read_b128 v[224:227], v197 offset:38912
	ds_read_b128 v[228:231], v197 offset:39936
	s_waitcnt lgkmcnt(8)
	s_barrier
	s_waitcnt lgkmcnt(0)
	v_mfma_f32_16x16x32_bf16 v[0:3], v[162:165], v[200:203], v[0:3]
	v_mfma_f32_16x16x32_bf16 v[126:129], v[170:173], v[200:203], v[126:129]
	v_mfma_f32_16x16x32_bf16 v[122:125], v[162:165], v[208:211], v[122:125]
	v_mfma_f32_16x16x32_bf16 v[118:121], v[170:173], v[208:211], v[118:121]
	v_mfma_f32_16x16x32_bf16 v[114:117], v[162:165], v[216:219], v[114:117]
	v_mfma_f32_16x16x32_bf16 v[110:113], v[170:173], v[216:219], v[110:113]
	v_mfma_f32_16x16x32_bf16 v[106:109], v[162:165], v[224:227], v[106:109]
	v_mfma_f32_16x16x32_bf16 v[102:105], v[170:173], v[224:227], v[102:105]
	v_mfma_f32_16x16x32_bf16 v[0:3], v[166:169], v[204:207], v[0:3]
	v_mfma_f32_16x16x32_bf16 v[126:129], v[174:177], v[204:207], v[126:129]
	v_mfma_f32_16x16x32_bf16 v[122:125], v[166:169], v[212:215], v[122:125]
	v_mfma_f32_16x16x32_bf16 v[118:121], v[174:177], v[212:215], v[118:121]
	v_mfma_f32_16x16x32_bf16 v[114:117], v[166:169], v[220:223], v[114:117]
	v_mfma_f32_16x16x32_bf16 v[110:113], v[174:177], v[220:223], v[110:113]
	v_mfma_f32_16x16x32_bf16 v[106:109], v[166:169], v[228:231], v[106:109]
	v_mfma_f32_16x16x32_bf16 v[102:105], v[174:177], v[228:231], v[102:105]
	v_add_u32_e32 v153, 0x80, v153
	v_add_u32_e32 v152, 0x80, v152
	s_add_i32 m0, s38, 0x18000
	s_barrier
	global_load_lds_dwordx4 v159, s[8:9]
	s_add_i32 m0, s38, 0x1a000
	ds_read_b128 v[232:235], v252
	global_load_lds_dwordx4 v158, s[8:9]
	ds_read_b128 v[236:239], v252 offset:1024
	ds_read_b128 v[240:243], v252 offset:2048
	ds_read_b128 v[244:247], v252 offset:3072
	s_barrier
	s_waitcnt lgkmcnt(0)
	v_mfma_f32_16x16x32_bf16 v[98:101], v[232:235], v[200:203], v[98:101]
	v_mfma_f32_16x16x32_bf16 v[94:97], v[240:243], v[200:203], v[94:97]
	v_mfma_f32_16x16x32_bf16 v[90:93], v[232:235], v[208:211], v[90:93]
	v_mfma_f32_16x16x32_bf16 v[86:89], v[240:243], v[208:211], v[86:89]
	v_mfma_f32_16x16x32_bf16 v[82:85], v[232:235], v[216:219], v[82:85]
	v_mfma_f32_16x16x32_bf16 v[78:81], v[240:243], v[216:219], v[78:81]
	v_mfma_f32_16x16x32_bf16 v[74:77], v[232:235], v[224:227], v[74:77]
	v_mfma_f32_16x16x32_bf16 v[70:73], v[240:243], v[224:227], v[70:73]
	v_mfma_f32_16x16x32_bf16 v[98:101], v[236:239], v[204:207], v[98:101]
	v_mfma_f32_16x16x32_bf16 v[94:97], v[244:247], v[204:207], v[94:97]
	v_mfma_f32_16x16x32_bf16 v[90:93], v[236:239], v[212:215], v[90:93]
	v_mfma_f32_16x16x32_bf16 v[86:89], v[244:247], v[212:215], v[86:89]
	v_mfma_f32_16x16x32_bf16 v[82:85], v[236:239], v[220:223], v[82:85]
	v_mfma_f32_16x16x32_bf16 v[78:81], v[244:247], v[220:223], v[78:81]
	v_mfma_f32_16x16x32_bf16 v[74:77], v[236:239], v[228:231], v[74:77]
	v_mfma_f32_16x16x32_bf16 v[70:73], v[244:247], v[228:231], v[70:73]
	v_add_u32_e32 v159, 0x80, v159
	v_add_u32_e32 v158, 0x80, v158
	s_add_i32 m0, s38, 0x8000
	s_barrier
	global_load_lds_dwordx4 v157, s[6:7]
	s_add_i32 m0, s38, 0xa000
	ds_read_b128 v[200:203], v197 offset:49152
	global_load_lds_dwordx4 v156, s[6:7]
	ds_read_b128 v[204:207], v197 offset:50176
	ds_read_b128 v[208:211], v197 offset:51200
	ds_read_b128 v[212:215], v197 offset:52224
	ds_read_b128 v[216:219], v197 offset:53248
	ds_read_b128 v[220:223], v197 offset:54272
	ds_read_b128 v[224:227], v197 offset:55296
	ds_read_b128 v[228:231], v197 offset:56320
	s_barrier
; #define LDA(dst, b, h) for (int m = 0; m < 4; ++m) for (int k = 0; k < 2; ++k) \
;     dst[m][k] = *reinterpret_cast<const bf16x8*>((char*)SA(b, h) + aoff + m * 2048 + k * 1024)
; #define LDB(dst, b, h) for (int n = 0; n < 2; ++n) for (int k = 0; k < 2; ++k) \
;     dst[n][k] = *reinterpret_cast<const bf16x8*>((char*)SB(b, h) + boff + n * 2048 + k * 1024)
; #define MMA(ai, bj, At, Bt) do { __builtin_amdgcn_s_setprio(1); \
;     for (int m = 0; m < 4; ++m) for (int n = 0; n < 2; ++n) for (int k = 0; k < 2; ++k) \
;       acc[ai][bj][m][n] = __builtin_amdgcn_mfma_f32_16x16x32_bf16(Bt[n][k], At[m][k], acc[ai][bj][m][n], 0, 0, 0); \
;     __builtin_amdgcn_s_setprio(0); } while (0)
; #define WAIT_V(n) asm volatile("s_waitcnt vmcnt(" #n ")" ::: "memory")
; #define WAIT_L(n) asm volatile("s_waitcnt lgkmcnt(" #n ")" ::: "memory")
; #define BAR __builtin_amdgcn_s_barrier()
; #define SCHED __builtin_amdgcn_sched_barrier(0)
; DEV void gemm_core(const u16* __restrict__ A, int lda, const u16* __restrict__ Bt, int ldb, int K,
;                    int brow, int bcol, f32x4 (&acc)[2][2][4][2]) {
;     ...
;     BAR; WAIT_L(0); MMA(1, 0, At, B0); BAR; SCHED;
;     STAGE(SB(1, 1), Bt, ldb, bcol + HALF, t + 3);
;     WAIT_V(6); BAR; MMA(1, 1, At, B1); BAR;
;   }
;   { LDB(B0, 0, 0); LDA(At, 0, 0); STAGE(SA(1, 1), A, lda, brow + HALF, nt - 1);
;     BAR; WAIT_L(0); MMA(0, 0, At, B0); BAR;
;     LDB(B1, 0, 1); BAR; WAIT_L(0); MMA(0, 1, At, B1); BAR;
	s_waitcnt lgkmcnt(0)
	v_mfma_f32_16x16x32_bf16 v[66:69], v[162:165], v[200:203], v[66:69]
	v_mfma_f32_16x16x32_bf16 v[62:65], v[170:173], v[200:203], v[62:65]
	v_mfma_f32_16x16x32_bf16 v[58:61], v[162:165], v[208:211], v[58:61]
	v_mfma_f32_16x16x32_bf16 v[54:57], v[170:173], v[208:211], v[54:57]
	v_mfma_f32_16x16x32_bf16 v[50:53], v[162:165], v[216:219], v[50:53]
	v_mfma_f32_16x16x32_bf16 v[46:49], v[170:173], v[216:219], v[46:49]
	v_mfma_f32_16x16x32_bf16 v[42:45], v[162:165], v[224:227], v[42:45]
	v_mfma_f32_16x16x32_bf16 v[38:41], v[170:173], v[224:227], v[38:41]
	v_mfma_f32_16x16x32_bf16 v[66:69], v[166:169], v[204:207], v[66:69]
	v_mfma_f32_16x16x32_bf16 v[62:65], v[174:177], v[204:207], v[62:65]
	v_mfma_f32_16x16x32_bf16 v[58:61], v[166:169], v[212:215], v[58:61]
	v_mfma_f32_16x16x32_bf16 v[54:57], v[174:177], v[212:215], v[54:57]
	v_mfma_f32_16x16x32_bf16 v[50:53], v[166:169], v[220:223], v[50:53]
	v_mfma_f32_16x16x32_bf16 v[46:49], v[174:177], v[220:223], v[46:49]
	v_mfma_f32_16x16x32_bf16 v[42:45], v[166:169], v[228:231], v[42:45]
	v_mfma_f32_16x16x32_bf16 v[38:41], v[174:177], v[228:231], v[38:41]
	v_add_u32_e32 v157, 0x80, v157
	v_add_u32_e32 v156, 0x80, v156
	s_add_i32 m0, s38, 0x1c000
	s_barrier
	global_load_lds_dwordx4 v155, s[8:9]
	s_add_i32 m0, s38, 0x1e000
	s_nop 0
	global_load_lds_dwordx4 v154, s[8:9]
	s_waitcnt vmcnt(6)
	s_barrier
	v_mfma_f32_16x16x32_bf16 v[34:37], v[232:235], v[200:203], v[34:37]
	v_mfma_f32_16x16x32_bf16 v[30:33], v[240:243], v[200:203], v[30:33]
	v_mfma_f32_16x16x32_bf16 v[26:29], v[232:235], v[208:211], v[26:29]
	v_mfma_f32_16x16x32_bf16 v[22:25], v[240:243], v[208:211], v[22:25]
	v_mfma_f32_16x16x32_bf16 v[18:21], v[232:235], v[216:219], v[18:21]
	v_mfma_f32_16x16x32_bf16 v[14:17], v[240:243], v[216:219], v[14:17]
	v_mfma_f32_16x16x32_bf16 v[10:13], v[232:235], v[224:227], v[10:13]
	v_mfma_f32_16x16x32_bf16 v[6:9], v[240:243], v[224:227], v[6:9]
	v_mfma_f32_16x16x32_bf16 v[34:37], v[236:239], v[204:207], v[34:37]
	v_mfma_f32_16x16x32_bf16 v[30:33], v[244:247], v[204:207], v[30:33]
	v_mfma_f32_16x16x32_bf16 v[26:29], v[236:239], v[212:215], v[26:29]
	v_mfma_f32_16x16x32_bf16 v[22:25], v[244:247], v[212:215], v[22:25]
	v_mfma_f32_16x16x32_bf16 v[18:21], v[236:239], v[220:223], v[18:21]
	v_mfma_f32_16x16x32_bf16 v[14:17], v[244:247], v[220:223], v[14:17]
	v_mfma_f32_16x16x32_bf16 v[10:13], v[236:239], v[228:231], v[10:13]
	v_mfma_f32_16x16x32_bf16 v[6:9], v[244:247], v[228:231], v[6:9]
	v_add_u32_e32 v155, 0x80, v155
	v_add_u32_e32 v154, 0x80, v154
	s_add_i32 m0, s38, 0xc000
	s_cmp_lt_i32 s36, s11
	s_barrier
	s_cbranch_scc1 .LBB0_191
	s_lshl_b32 s8, s13, 7
	v_add_u32_e32 v190, 16, v182
	s_add_i32 s10, s10, s8
	v_add_u32_e32 v4, 0x10000, v190
	s_and_b32 s8, s12, 0x1fc0
	ds_read_b128 v[130:133], v4
	ds_read_b128 v[134:137], v4 offset:1024
	ds_read_b128 v[150:153], v4 offset:2048
	ds_read_b128 v[154:157], v4 offset:3072
	s_add_i32 s8, s8, s10
	v_or_b32_e32 v4, 0xffffffc0, v142
	v_add_u32_e32 v140, s8, v4
	v_add_u32_e32 v4, v140, v149
	v_readfirstlane_b32 s8, v160
	v_lshl_add_u64 v[138:139], v[4:5], 1, s[6:7]
	s_mov_b32 m0, s8
	v_add_u32_e32 v4, v140, v141
	global_load_lds_dwordx4 v[138:139], off
	v_lshl_add_u64 v[138:139], v[4:5], 1, s[6:7]
	v_readfirstlane_b32 s6, v161
	s_mov_b32 m0, s6
	s_nop 0
	global_load_lds_dwordx4 v[138:139], off
	ds_read_b128 v[138:141], v197
	ds_read_b128 v[158:161], v197 offset:1024
	ds_read_b128 v[162:165], v197 offset:2048
	ds_read_b128 v[166:169], v197 offset:3072
	ds_read_b128 v[170:173], v197 offset:4096
	ds_read_b128 v[174:177], v197 offset:5120
	ds_read_b128 v[200:203], v197 offset:6144
	ds_read_b128 v[204:207], v197 offset:7168
	s_barrier
	s_waitcnt lgkmcnt(0)
	s_setprio 1
	s_waitcnt lgkmcnt(0)
	v_mfma_f32_16x16x32_bf16 v[0:3], v[130:133], v[138:141], v[0:3]
	v_mfma_f32_16x16x32_bf16 v[126:129], v[150:153], v[138:141], v[126:129]
	v_mfma_f32_16x16x32_bf16 v[122:125], v[130:133], v[162:165], v[122:125]
	v_mfma_f32_16x16x32_bf16 v[118:121], v[150:153], v[162:165], v[118:121]
	v_mfma_f32_16x16x32_bf16 v[114:117], v[130:133], v[170:173], v[114:117]
	v_mfma_f32_16x16x32_bf16 v[110:113], v[150:153], v[170:173], v[110:113]
	v_mfma_f32_16x16x32_bf16 v[106:109], v[130:133], v[200:203], v[106:109]
	v_mfma_f32_16x16x32_bf16 v[102:105], v[150:153], v[200:203], v[102:105]
	v_mfma_f32_16x16x32_bf16 v[0:3], v[134:137], v[158:161], v[0:3]
	v_mfma_f32_16x16x32_bf16 v[126:129], v[154:157], v[158:161], v[126:129]
	v_mfma_f32_16x16x32_bf16 v[122:125], v[134:137], v[166:169], v[122:125]
	v_mfma_f32_16x16x32_bf16 v[118:121], v[154:157], v[166:169], v[118:121]
	v_mfma_f32_16x16x32_bf16 v[114:117], v[134:137], v[174:177], v[114:117]
	v_mfma_f32_16x16x32_bf16 v[110:113], v[154:157], v[174:177], v[110:113]
	v_mfma_f32_16x16x32_bf16 v[106:109], v[134:137], v[204:207], v[106:109]
	v_mfma_f32_16x16x32_bf16 v[102:105], v[154:157], v[204:207], v[102:105]
	s_setprio 0
	v_add_u32_e32 v4, 0x14000, v190
	s_barrier
	ds_read_b128 v[208:211], v4
	ds_read_b128 v[212:215], v4 offset:1024
	ds_read_b128 v[216:219], v4 offset:2048
	ds_read_b128 v[220:223], v4 offset:3072
	s_barrier
; #define LDA(dst, b, h) for (int m = 0; m < 4; ++m) for (int k = 0; k < 2; ++k) \
;     dst[m][k] = *reinterpret_cast<const bf16x8*>((char*)SA(b, h) + aoff + m * 2048 + k * 1024)
; #define LDB(dst, b, h) for (int n = 0; n < 2; ++n) for (int k = 0; k < 2; ++k) \
;     dst[n][k] = *reinterpret_cast<const bf16x8*>((char*)SB(b, h) + boff + n * 2048 + k * 1024)
; #define MMA(ai, bj, At, Bt) do { __builtin_amdgcn_s_setprio(1); \
;     for (int m = 0; m < 4; ++m) for (int n = 0; n < 2; ++n) for (int k = 0; k < 2; ++k) \
;       acc[ai][bj][m][n] = __builtin_amdgcn_mfma_f32_16x16x32_bf16(Bt[n][k], At[m][k], acc[ai][bj][m][n], 0, 0, 0); \
;     __builtin_amdgcn_s_setprio(0); } while (0)
; #define WAIT_V(n) asm volatile("s_waitcnt vmcnt(" #n ")" ::: "memory")
; #define WAIT_L(n) asm volatile("s_waitcnt lgkmcnt(" #n ")" ::: "memory")
; #define BAR __builtin_amdgcn_s_barrier()
; DEV void gemm_core(const u16* __restrict__ A, int lda, const u16* __restrict__ Bt, int ldb, int K,
;                    int brow, int bcol, f32x4 (&acc)[2][2][4][2]) {
;     ...
;     LDB(B1, 0, 1); BAR; WAIT_L(0); MMA(0, 1, At, B1); BAR;
;     LDA(At, 0, 1); WAIT_V(4); BAR; WAIT_L(0); MMA(1, 0, At, B0); MMA(1, 1, At, B1); BAR; }
;   { LDB(B0, 1, 0); LDA(At, 1, 0); WAIT_V(2); BAR; WAIT_L(0); MMA(0, 0, At, B0); BAR;
	s_waitcnt lgkmcnt(0)
	s_setprio 1
	s_waitcnt lgkmcnt(0)
	v_mfma_f32_16x16x32_bf16 v[98:101], v[208:211], v[138:141], v[98:101]
	v_mfma_f32_16x16x32_bf16 v[94:97], v[216:219], v[138:141], v[94:97]
	v_mfma_f32_16x16x32_bf16 v[90:93], v[208:211], v[162:165], v[90:93]
	v_mfma_f32_16x16x32_bf16 v[86:89], v[216:219], v[162:165], v[86:89]
	v_mfma_f32_16x16x32_bf16 v[82:85], v[208:211], v[170:173], v[82:85]
	v_mfma_f32_16x16x32_bf16 v[78:81], v[216:219], v[170:173], v[78:81]
	v_mfma_f32_16x16x32_bf16 v[74:77], v[208:211], v[200:203], v[74:77]
	v_mfma_f32_16x16x32_bf16 v[70:73], v[216:219], v[200:203], v[70:73]
	v_mfma_f32_16x16x32_bf16 v[98:101], v[212:215], v[158:161], v[98:101]
	v_mfma_f32_16x16x32_bf16 v[94:97], v[220:223], v[158:161], v[94:97]
	v_mfma_f32_16x16x32_bf16 v[90:93], v[212:215], v[166:169], v[90:93]
	v_mfma_f32_16x16x32_bf16 v[86:89], v[220:223], v[166:169], v[86:89]
	v_mfma_f32_16x16x32_bf16 v[82:85], v[212:215], v[174:177], v[82:85]
	v_mfma_f32_16x16x32_bf16 v[78:81], v[220:223], v[174:177], v[78:81]
	v_mfma_f32_16x16x32_bf16 v[74:77], v[212:215], v[204:207], v[74:77]
	v_mfma_f32_16x16x32_bf16 v[70:73], v[220:223], v[204:207], v[70:73]
	s_setprio 0
	s_barrier
	ds_read_b128 v[138:141], v197 offset:16384
	ds_read_b128 v[158:161], v197 offset:17408
	ds_read_b128 v[162:165], v197 offset:18432
	ds_read_b128 v[166:169], v197 offset:19456
	ds_read_b128 v[170:173], v197 offset:20480
	ds_read_b128 v[174:177], v197 offset:21504
	ds_read_b128 v[200:203], v197 offset:22528
	ds_read_b128 v[204:207], v197 offset:23552
	s_waitcnt vmcnt(4)
	s_barrier
	s_waitcnt lgkmcnt(0)
	s_setprio 1
	s_waitcnt lgkmcnt(0)
	v_mfma_f32_16x16x32_bf16 v[66:69], v[130:133], v[138:141], v[66:69]
	v_mfma_f32_16x16x32_bf16 v[62:65], v[150:153], v[138:141], v[62:65]
	v_mfma_f32_16x16x32_bf16 v[58:61], v[130:133], v[162:165], v[58:61]
	v_mfma_f32_16x16x32_bf16 v[54:57], v[150:153], v[162:165], v[54:57]
	v_mfma_f32_16x16x32_bf16 v[50:53], v[130:133], v[170:173], v[50:53]
	v_mfma_f32_16x16x32_bf16 v[46:49], v[150:153], v[170:173], v[46:49]
	v_mfma_f32_16x16x32_bf16 v[42:45], v[130:133], v[200:203], v[42:45]
	v_mfma_f32_16x16x32_bf16 v[38:41], v[150:153], v[200:203], v[38:41]
	v_mfma_f32_16x16x32_bf16 v[66:69], v[134:137], v[158:161], v[66:69]
	v_mfma_f32_16x16x32_bf16 v[62:65], v[154:157], v[158:161], v[62:65]
	v_mfma_f32_16x16x32_bf16 v[58:61], v[134:137], v[166:169], v[58:61]
	v_mfma_f32_16x16x32_bf16 v[54:57], v[154:157], v[166:169], v[54:57]
	v_mfma_f32_16x16x32_bf16 v[50:53], v[134:137], v[174:177], v[50:53]
	v_mfma_f32_16x16x32_bf16 v[46:49], v[154:157], v[174:177], v[46:49]
	v_mfma_f32_16x16x32_bf16 v[42:45], v[134:137], v[204:207], v[42:45]
	v_mfma_f32_16x16x32_bf16 v[38:41], v[154:157], v[204:207], v[38:41]
	s_setprio 0
	s_setprio 1
	v_mfma_f32_16x16x32_bf16 v[34:37], v[208:211], v[138:141], v[34:37]
	v_mfma_f32_16x16x32_bf16 v[30:33], v[216:219], v[138:141], v[30:33]
	v_mfma_f32_16x16x32_bf16 v[26:29], v[208:211], v[162:165], v[26:29]
	v_mfma_f32_16x16x32_bf16 v[22:25], v[216:219], v[162:165], v[22:25]
	v_mfma_f32_16x16x32_bf16 v[18:21], v[208:211], v[170:173], v[18:21]
	v_mfma_f32_16x16x32_bf16 v[14:17], v[216:219], v[170:173], v[14:17]
	v_mfma_f32_16x16x32_bf16 v[10:13], v[208:211], v[200:203], v[10:13]
	v_mfma_f32_16x16x32_bf16 v[6:9], v[216:219], v[200:203], v[6:9]
	v_mfma_f32_16x16x32_bf16 v[34:37], v[212:215], v[158:161], v[34:37]
	v_mfma_f32_16x16x32_bf16 v[30:33], v[220:223], v[158:161], v[30:33]
	v_mfma_f32_16x16x32_bf16 v[26:29], v[212:215], v[166:169], v[26:29]
	v_mfma_f32_16x16x32_bf16 v[22:25], v[220:223], v[166:169], v[22:25]
	v_mfma_f32_16x16x32_bf16 v[18:21], v[212:215], v[174:177], v[18:21]
	v_mfma_f32_16x16x32_bf16 v[14:17], v[220:223], v[174:177], v[14:17]
	v_mfma_f32_16x16x32_bf16 v[10:13], v[212:215], v[204:207], v[10:13]
	v_mfma_f32_16x16x32_bf16 v[6:9], v[220:223], v[204:207], v[6:9]
	s_setprio 0
	v_add_u32_e32 v4, 0x18000, v190
	s_barrier
	ds_read_b128 v[130:133], v4
	ds_read_b128 v[134:137], v4 offset:1024
	ds_read_b128 v[138:141], v4 offset:2048
	ds_read_b128 v[148:151], v4 offset:3072
	ds_read_b128 v[152:155], v197 offset:32768
	ds_read_b128 v[156:159], v197 offset:33792
	ds_read_b128 v[160:163], v197 offset:34816
	ds_read_b128 v[164:167], v197 offset:35840
	ds_read_b128 v[168:171], v197 offset:36864
	ds_read_b128 v[172:175], v197 offset:37888
	ds_read_b128 v[200:203], v197 offset:38912
	ds_read_b128 v[204:207], v197 offset:39936
	s_waitcnt vmcnt(2)
	s_barrier
; #define LDA(dst, b, h) for (int m = 0; m < 4; ++m) for (int k = 0; k < 2; ++k) \
;     dst[m][k] = *reinterpret_cast<const bf16x8*>((char*)SA(b, h) + aoff + m * 2048 + k * 1024)
; #define LDB(dst, b, h) for (int n = 0; n < 2; ++n) for (int k = 0; k < 2; ++k) \
;     dst[n][k] = *reinterpret_cast<const bf16x8*>((char*)SB(b, h) + boff + n * 2048 + k * 1024)
; #define MMA(ai, bj, At, Bt) do { __builtin_amdgcn_s_setprio(1); \
;     for (int m = 0; m < 4; ++m) for (int n = 0; n < 2; ++n) for (int k = 0; k < 2; ++k) \
;       acc[ai][bj][m][n] = __builtin_amdgcn_mfma_f32_16x16x32_bf16(Bt[n][k], At[m][k], acc[ai][bj][m][n], 0, 0, 0); \
;     __builtin_amdgcn_s_setprio(0); } while (0)
; #define WAIT_V(n) asm volatile("s_waitcnt vmcnt(" #n ")" ::: "memory")
; #define WAIT_L(n) asm volatile("s_waitcnt lgkmcnt(" #n ")" ::: "memory")
; #define BAR __builtin_amdgcn_s_barrier()
; DEV void gemm_core(const u16* __restrict__ A, int lda, const u16* __restrict__ Bt, int ldb, int K,
;                    int brow, int bcol, f32x4 (&acc)[2][2][4][2]) {
;     ...
;   { LDB(B0, 1, 0); LDA(At, 1, 0); WAIT_V(2); BAR; WAIT_L(0); MMA(0, 0, At, B0); BAR;
;     LDB(B1, 1, 1); WAIT_V(0); BAR; WAIT_L(0); MMA(0, 1, At, B1); BAR;
;     LDA(At, 1, 1); BAR; WAIT_L(0); MMA(1, 0, At, B0); MMA(1, 1, At, B1); BAR; }
;   if (wr == 0) BAR;
	s_waitcnt lgkmcnt(0)
	s_setprio 1
	s_waitcnt lgkmcnt(0)
	v_mfma_f32_16x16x32_bf16 v[0:3], v[130:133], v[152:155], v[0:3]
	v_mfma_f32_16x16x32_bf16 v[126:129], v[138:141], v[152:155], v[126:129]
	v_mfma_f32_16x16x32_bf16 v[122:125], v[130:133], v[160:163], v[122:125]
	v_mfma_f32_16x16x32_bf16 v[118:121], v[138:141], v[160:163], v[118:121]
	v_mfma_f32_16x16x32_bf16 v[114:117], v[130:133], v[168:171], v[114:117]
	v_mfma_f32_16x16x32_bf16 v[110:113], v[138:141], v[168:171], v[110:113]
	v_mfma_f32_16x16x32_bf16 v[106:109], v[130:133], v[200:203], v[106:109]
	v_mfma_f32_16x16x32_bf16 v[102:105], v[138:141], v[200:203], v[102:105]
	v_mfma_f32_16x16x32_bf16 v[0:3], v[134:137], v[156:159], v[0:3]
	v_mfma_f32_16x16x32_bf16 v[126:129], v[148:151], v[156:159], v[126:129]
	v_mfma_f32_16x16x32_bf16 v[122:125], v[134:137], v[164:167], v[122:125]
	v_mfma_f32_16x16x32_bf16 v[118:121], v[148:151], v[164:167], v[118:121]
	v_mfma_f32_16x16x32_bf16 v[114:117], v[134:137], v[172:175], v[114:117]
	v_mfma_f32_16x16x32_bf16 v[110:113], v[148:151], v[172:175], v[110:113]
	v_mfma_f32_16x16x32_bf16 v[106:109], v[134:137], v[204:207], v[106:109]
	v_mfma_f32_16x16x32_bf16 v[102:105], v[148:151], v[204:207], v[102:105]
	s_setprio 0
	v_add_u32_e32 v4, 0x1c000, v190
	s_barrier
	ds_read_b128 v[208:211], v4
	ds_read_b128 v[212:215], v4 offset:1024
	ds_read_b128 v[216:219], v4 offset:2048
	ds_read_b128 v[220:223], v4 offset:3072
	s_waitcnt vmcnt(0)
	s_barrier
	s_waitcnt lgkmcnt(0)
	s_setprio 1
	s_waitcnt lgkmcnt(0)
	v_mfma_f32_16x16x32_bf16 v[98:101], v[208:211], v[152:155], v[98:101]
	v_mfma_f32_16x16x32_bf16 v[94:97], v[216:219], v[152:155], v[94:97]
	v_mfma_f32_16x16x32_bf16 v[90:93], v[208:211], v[160:163], v[90:93]
	v_mfma_f32_16x16x32_bf16 v[86:89], v[216:219], v[160:163], v[86:89]
	v_mfma_f32_16x16x32_bf16 v[82:85], v[208:211], v[168:171], v[82:85]
	v_mfma_f32_16x16x32_bf16 v[78:81], v[216:219], v[168:171], v[78:81]
	v_mfma_f32_16x16x32_bf16 v[74:77], v[208:211], v[200:203], v[74:77]
	v_mfma_f32_16x16x32_bf16 v[70:73], v[216:219], v[200:203], v[70:73]
	v_mfma_f32_16x16x32_bf16 v[98:101], v[212:215], v[156:159], v[98:101]
	v_mfma_f32_16x16x32_bf16 v[94:97], v[220:223], v[156:159], v[94:97]
	v_mfma_f32_16x16x32_bf16 v[90:93], v[212:215], v[164:167], v[90:93]
	v_mfma_f32_16x16x32_bf16 v[86:89], v[220:223], v[164:167], v[86:89]
	v_mfma_f32_16x16x32_bf16 v[82:85], v[212:215], v[172:175], v[82:85]
	v_mfma_f32_16x16x32_bf16 v[78:81], v[220:223], v[172:175], v[78:81]
	v_mfma_f32_16x16x32_bf16 v[74:77], v[212:215], v[204:207], v[74:77]
	v_mfma_f32_16x16x32_bf16 v[70:73], v[220:223], v[204:207], v[70:73]
	s_setprio 0
	s_barrier
	ds_read_b128 v[152:155], v197 offset:49152
	ds_read_b128 v[156:159], v197 offset:50176
	ds_read_b128 v[160:163], v197 offset:51200
	ds_read_b128 v[164:167], v197 offset:52224
	ds_read_b128 v[168:171], v197 offset:53248
	ds_read_b128 v[172:175], v197 offset:54272
	ds_read_b128 v[200:203], v197 offset:55296
	ds_read_b128 v[204:207], v197 offset:56320
	s_barrier
	s_waitcnt lgkmcnt(0)
	s_setprio 1
	s_waitcnt lgkmcnt(0)
	v_mfma_f32_16x16x32_bf16 v[66:69], v[130:133], v[152:155], v[66:69]
	v_mfma_f32_16x16x32_bf16 v[62:65], v[138:141], v[152:155], v[62:65]
	v_mfma_f32_16x16x32_bf16 v[58:61], v[130:133], v[160:163], v[58:61]
	v_mfma_f32_16x16x32_bf16 v[54:57], v[138:141], v[160:163], v[54:57]
	v_mfma_f32_16x16x32_bf16 v[50:53], v[130:133], v[168:171], v[50:53]
	v_mfma_f32_16x16x32_bf16 v[46:49], v[138:141], v[168:171], v[46:49]
	v_mfma_f32_16x16x32_bf16 v[42:45], v[130:133], v[200:203], v[42:45]
	v_mfma_f32_16x16x32_bf16 v[38:41], v[138:141], v[200:203], v[38:41]
	v_mfma_f32_16x16x32_bf16 v[66:69], v[134:137], v[156:159], v[66:69]
	v_mfma_f32_16x16x32_bf16 v[62:65], v[148:151], v[156:159], v[62:65]
	v_mfma_f32_16x16x32_bf16 v[58:61], v[134:137], v[164:167], v[58:61]
	v_mfma_f32_16x16x32_bf16 v[54:57], v[148:151], v[164:167], v[54:57]
	v_mfma_f32_16x16x32_bf16 v[50:53], v[134:137], v[172:175], v[50:53]
	v_mfma_f32_16x16x32_bf16 v[46:49], v[148:151], v[172:175], v[46:49]
	v_mfma_f32_16x16x32_bf16 v[42:45], v[134:137], v[204:207], v[42:45]
	v_mfma_f32_16x16x32_bf16 v[38:41], v[148:151], v[204:207], v[38:41]
	s_setprio 0
	s_setprio 1
	v_mfma_f32_16x16x32_bf16 v[34:37], v[208:211], v[152:155], v[34:37]
	v_mfma_f32_16x16x32_bf16 v[30:33], v[216:219], v[152:155], v[30:33]
	v_mfma_f32_16x16x32_bf16 v[26:29], v[208:211], v[160:163], v[26:29]
	v_mfma_f32_16x16x32_bf16 v[22:25], v[216:219], v[160:163], v[22:25]
	v_mfma_f32_16x16x32_bf16 v[18:21], v[208:211], v[168:171], v[18:21]
	v_mfma_f32_16x16x32_bf16 v[14:17], v[216:219], v[168:171], v[14:17]
	v_mfma_f32_16x16x32_bf16 v[10:13], v[208:211], v[200:203], v[10:13]
	v_mfma_f32_16x16x32_bf16 v[6:9], v[216:219], v[200:203], v[6:9]
	v_mfma_f32_16x16x32_bf16 v[34:37], v[212:215], v[156:159], v[34:37]
	v_mfma_f32_16x16x32_bf16 v[30:33], v[220:223], v[156:159], v[30:33]
	v_mfma_f32_16x16x32_bf16 v[26:29], v[212:215], v[164:167], v[26:29]
	v_mfma_f32_16x16x32_bf16 v[22:25], v[220:223], v[164:167], v[22:25]
	v_mfma_f32_16x16x32_bf16 v[18:21], v[212:215], v[172:175], v[18:21]
	v_mfma_f32_16x16x32_bf16 v[14:17], v[220:223], v[172:175], v[14:17]
	v_mfma_f32_16x16x32_bf16 v[10:13], v[212:215], v[204:207], v[10:13]
	v_mfma_f32_16x16x32_bf16 v[6:9], v[220:223], v[204:207], v[6:9]
	s_setprio 0
	s_barrier
	s_mov_b64 s[6:7], exec
	v_readlane_b32 s8, v254, 51
	v_readlane_b32 s9, v254, 52
	s_and_b64 s[8:9], s[6:7], s[8:9]
	s_mov_b64 exec, s[8:9]
	s_cbranch_execz .LBB0_194
	s_barrier
